# de-serialised latency chains: P0 silu staging 9 loads in flight, first-barrier census loads pipelined, up-proj epilogue canonicalising v_max removed (on top of ctx remap + D park)
# speedup vs baseline: 1.0156x; 1.0156x over previous
.LBB0_39:
	s_lshl_b32 s6, s62, 8
	s_ashr_i32 s7, s6, 31
	s_lshl_b64 s[6:7], s[6:7], 14
	s_add_u32 s8, s20, s6
	s_addc_u32 s9, s21, s7
	s_lshl_b32 s6, s59, 8
	v_max_f32_e32 v122, 0, v122
	v_mov_b32_e32 v0, v145
	s_ashr_i32 s7, s6, 31
	v_mul_f32_e32 v147, v122, v122
	v_max_f32_e32 v123, 0, v123
	v_max_f32_e32 v124, 0, v124
	s_lshl_b64 s[6:7], s[6:7], 1
	v_and_or_b32 v142, v0, 15, s38
	v_max_f32_e32 v122, 0, v127
	v_mul_f32_e32 v127, v123, v123
	v_max_f32_e32 v123, v128, v128
	v_mul_f32_e32 v128, v124, v124
	s_add_u32 s6, s8, s6
	v_lshlrev_b32_e32 v142, 14, v142
	v_and_b32_e32 v0, -16, v0
	v_max_f32_e32 v126, 0, v126
	v_mul_f32_e32 v122, v122, v122
	v_max_f32_e32 v123, 0, v123
	v_max_f32_e32 v124, 0, v129
	v_max_f32_e32 v125, 0, v125
	s_addc_u32 s7, s9, s7
	v_add3_u32 v0, v0, s57, v142
	v_mul_f32_e32 v126, v126, v126
	v_mul_f32_e32 v123, v123, v123
	v_mul_f32_e32 v124, v124, v124
	v_mul_f32_e32 v125, v125, v125
	v_cvt_pk_bf16_f32 v122, v126, v122
	v_max_f32_e32 v114, 0, v114
	v_max_f32_e32 v115, 0, v115
	v_max_f32_e32 v116, 0, v116
	v_cvt_pk_bf16_f32 v123, v123, v124
	v_cvt_pk_bf16_f32 v124, v147, v127
	v_cvt_pk_bf16_f32 v125, v128, v125
	global_store_dwordx4 v0, v[122:125], s[6:7]
	s_nop 1
	v_mul_f32_e32 v122, v114, v114
	v_max_f32_e32 v114, v119, v119
	v_mul_f32_e32 v119, v115, v115
	v_max_f32_e32 v115, v120, v120
	v_mul_f32_e32 v120, v116, v116
	v_max_f32_e32 v114, 0, v114
	v_max_f32_e32 v115, 0, v115
	v_max_f32_e32 v116, 0, v121
	v_max_f32_e32 v117, 0, v117
	v_max_f32_e32 v118, 0, v118
	v_mul_f32_e32 v114, v114, v114
	v_mul_f32_e32 v115, v115, v115
	v_mul_f32_e32 v116, v116, v116
	v_mul_f32_e32 v117, v117, v117
	v_max_f32_e32 v106, 0, v106
	v_lshl_add_u64 v[142:143], s[6:7], 0, v[0:1]
	v_mul_f32_e32 v118, v118, v118
	v_cvt_pk_bf16_f32 v114, v118, v114
	v_cvt_pk_bf16_f32 v115, v115, v116
	v_cvt_pk_bf16_f32 v116, v122, v119
	v_cvt_pk_bf16_f32 v117, v120, v117
	global_store_dwordx4 v0, v[114:117], s[6:7] offset:256
	s_nop 1
	v_max_f32_e32 v0, v110, v110
	v_mul_f32_e32 v110, v106, v106
	v_max_f32_e32 v107, 0, v107
	v_max_f32_e32 v108, 0, v108
	v_max_f32_e32 v0, 0, v0
	v_max_f32_e32 v106, 0, v111
	v_mul_f32_e32 v111, v107, v107
	v_max_f32_e32 v107, v112, v112
	v_mul_f32_e32 v112, v108, v108
	v_mul_f32_e32 v0, v0, v0
	v_mul_f32_e32 v106, v106, v106
	v_max_f32_e32 v107, 0, v107
	v_max_f32_e32 v108, 0, v113
	v_max_f32_e32 v98, 0, v98
	v_mul_f32_e32 v107, v107, v107
	v_mul_f32_e32 v108, v108, v108
	v_cvt_pk_bf16_f32 v106, v0, v106
	s_mov_b32 s6, 0x40000
	v_max_f32_e32 v0, v102, v102
	v_mul_f32_e32 v102, v98, v98
	v_max_f32_e32 v109, 0, v109
	v_cvt_pk_bf16_f32 v107, v107, v108
	v_cvt_pk_bf16_f32 v108, v110, v111
	v_add_co_u32_e32 v110, vcc, s6, v142
	v_max_f32_e32 v0, 0, v0
	v_max_f32_e32 v98, 0, v103
	v_mul_f32_e32 v109, v109, v109
	v_addc_co_u32_e32 v111, vcc, 0, v143, vcc
	v_mul_f32_e32 v0, v0, v0
	v_max_f32_e32 v99, 0, v99
	v_mul_f32_e32 v98, v98, v98
	v_max_f32_e32 v100, 0, v100
	v_max_f32_e32 v90, 0, v90
	v_cvt_pk_bf16_f32 v109, v112, v109
	global_store_dwordx4 v[110:111], v[106:109], off
	s_nop 1
	v_mul_f32_e32 v103, v99, v99
	v_max_f32_e32 v99, v104, v104
	v_mul_f32_e32 v104, v100, v100
	v_cvt_pk_bf16_f32 v98, v0, v98
	v_max_f32_e32 v0, v94, v94
	v_mul_f32_e32 v94, v90, v90
	v_max_f32_e32 v91, 0, v91
	v_max_f32_e32 v92, 0, v92
	v_max_f32_e32 v99, 0, v99
	v_max_f32_e32 v100, 0, v105
	v_max_f32_e32 v101, 0, v101
	v_max_f32_e32 v0, 0, v0
	v_max_f32_e32 v90, 0, v95
	v_mul_f32_e32 v95, v91, v91
	v_max_f32_e32 v91, v96, v96
	v_mul_f32_e32 v96, v92, v92
	v_mul_f32_e32 v99, v99, v99
	v_mul_f32_e32 v100, v100, v100
	v_mul_f32_e32 v101, v101, v101
	v_mul_f32_e32 v0, v0, v0
	v_mul_f32_e32 v90, v90, v90
	v_max_f32_e32 v91, 0, v91
	v_max_f32_e32 v92, 0, v97
	v_max_f32_e32 v82, 0, v82
	v_cvt_pk_bf16_f32 v99, v99, v100
	v_cvt_pk_bf16_f32 v100, v102, v103
	v_cvt_pk_bf16_f32 v101, v104, v101
	global_store_dwordx4 v[110:111], v[98:101], off offset:256
	s_nop 1
	v_mul_f32_e32 v91, v91, v91
	v_mul_f32_e32 v92, v92, v92
	v_cvt_pk_bf16_f32 v90, v0, v90
	s_mov_b32 s6, 0x80000
	v_max_f32_e32 v0, v86, v86
	v_mul_f32_e32 v86, v82, v82
	v_max_f32_e32 v93, 0, v93
	v_cvt_pk_bf16_f32 v91, v91, v92
	v_cvt_pk_bf16_f32 v92, v94, v95
	v_add_co_u32_e32 v94, vcc, s6, v142
	v_max_f32_e32 v0, 0, v0
	v_max_f32_e32 v82, 0, v87
	v_mul_f32_e32 v93, v93, v93
	v_addc_co_u32_e32 v95, vcc, 0, v143, vcc
	v_mul_f32_e32 v0, v0, v0
	v_max_f32_e32 v83, 0, v83
	v_mul_f32_e32 v82, v82, v82
	v_max_f32_e32 v84, 0, v84
	v_max_f32_e32 v74, 0, v74
	v_cvt_pk_bf16_f32 v93, v96, v93
	global_store_dwordx4 v[94:95], v[90:93], off
	s_nop 1
	v_mul_f32_e32 v87, v83, v83
	v_max_f32_e32 v83, v88, v88
	v_mul_f32_e32 v88, v84, v84
	v_cvt_pk_bf16_f32 v82, v0, v82
	v_max_f32_e32 v0, v78, v78
	v_mul_f32_e32 v78, v74, v74
	v_max_f32_e32 v75, 0, v75
	v_max_f32_e32 v76, 0, v76
	v_max_f32_e32 v83, 0, v83
	v_max_f32_e32 v84, 0, v89
	v_max_f32_e32 v85, 0, v85
	v_max_f32_e32 v0, 0, v0
	v_max_f32_e32 v74, 0, v79
	v_mul_f32_e32 v79, v75, v75
	v_max_f32_e32 v75, v80, v80
	v_mul_f32_e32 v80, v76, v76
	v_mul_f32_e32 v83, v83, v83
	v_mul_f32_e32 v84, v84, v84
	v_mul_f32_e32 v85, v85, v85
	v_mul_f32_e32 v0, v0, v0
	v_mul_f32_e32 v74, v74, v74
	v_max_f32_e32 v75, 0, v75
	v_max_f32_e32 v76, 0, v81
	v_max_f32_e32 v66, 0, v66
	v_cvt_pk_bf16_f32 v83, v83, v84
	v_cvt_pk_bf16_f32 v84, v86, v87
	v_cvt_pk_bf16_f32 v85, v88, v85
	global_store_dwordx4 v[94:95], v[82:85], off offset:256
	s_nop 1
	v_mul_f32_e32 v75, v75, v75
	v_mul_f32_e32 v76, v76, v76
	v_cvt_pk_bf16_f32 v74, v0, v74
	s_mov_b32 s6, 0xc0000
	v_max_f32_e32 v0, v70, v70
	v_mul_f32_e32 v70, v66, v66
	v_max_f32_e32 v77, 0, v77
	v_cvt_pk_bf16_f32 v75, v75, v76
	v_cvt_pk_bf16_f32 v76, v78, v79
	v_add_co_u32_e32 v78, vcc, s6, v142
	v_max_f32_e32 v0, 0, v0
	v_max_f32_e32 v66, 0, v71
	v_mul_f32_e32 v77, v77, v77
	v_addc_co_u32_e32 v79, vcc, 0, v143, vcc
	v_mul_f32_e32 v0, v0, v0
	v_max_f32_e32 v67, 0, v67
	v_mul_f32_e32 v66, v66, v66
	v_max_f32_e32 v68, 0, v68
	v_max_f32_e32 v58, 0, v58
	v_cvt_pk_bf16_f32 v77, v80, v77
	global_store_dwordx4 v[78:79], v[74:77], off
	s_nop 1
	v_mul_f32_e32 v71, v67, v67
	v_max_f32_e32 v67, v72, v72
	v_mul_f32_e32 v72, v68, v68
	v_cvt_pk_bf16_f32 v66, v0, v66
	v_max_f32_e32 v0, v62, v62
	v_mul_f32_e32 v62, v58, v58
	v_max_f32_e32 v59, 0, v59
	v_max_f32_e32 v60, 0, v60
	v_max_f32_e32 v67, 0, v67
	v_max_f32_e32 v68, 0, v73
	v_max_f32_e32 v69, 0, v69
	v_max_f32_e32 v0, 0, v0
	v_max_f32_e32 v58, 0, v63
	v_mul_f32_e32 v63, v59, v59
	v_max_f32_e32 v59, v64, v64
	v_mul_f32_e32 v64, v60, v60
	v_mul_f32_e32 v67, v67, v67
	v_mul_f32_e32 v68, v68, v68
	v_mul_f32_e32 v69, v69, v69
	v_mul_f32_e32 v0, v0, v0
	v_mul_f32_e32 v58, v58, v58
	v_max_f32_e32 v59, 0, v59
	v_max_f32_e32 v60, 0, v65
	v_max_f32_e32 v50, 0, v50
	v_cvt_pk_bf16_f32 v67, v67, v68
	v_cvt_pk_bf16_f32 v68, v70, v71
	v_cvt_pk_bf16_f32 v69, v72, v69
	global_store_dwordx4 v[78:79], v[66:69], off offset:256
	s_nop 1
	v_mul_f32_e32 v59, v59, v59
	v_mul_f32_e32 v60, v60, v60
	v_cvt_pk_bf16_f32 v58, v0, v58
	s_mov_b32 s6, 0x200000
	v_max_f32_e32 v0, v54, v54
	v_mul_f32_e32 v54, v50, v50
	v_max_f32_e32 v61, 0, v61
	v_cvt_pk_bf16_f32 v59, v59, v60
	v_cvt_pk_bf16_f32 v60, v62, v63
	v_add_co_u32_e32 v62, vcc, s6, v142
	v_max_f32_e32 v0, 0, v0
	v_max_f32_e32 v50, 0, v55
	v_mul_f32_e32 v61, v61, v61
	v_addc_co_u32_e32 v63, vcc, 0, v143, vcc
	v_mul_f32_e32 v0, v0, v0
	v_max_f32_e32 v51, 0, v51
	v_mul_f32_e32 v50, v50, v50
	v_max_f32_e32 v52, 0, v52
	v_max_f32_e32 v42, 0, v42
	v_cvt_pk_bf16_f32 v61, v64, v61
	global_store_dwordx4 v[62:63], v[58:61], off
	s_nop 1
	v_mul_f32_e32 v55, v51, v51
	v_max_f32_e32 v51, v56, v56
	v_mul_f32_e32 v56, v52, v52
	v_cvt_pk_bf16_f32 v50, v0, v50
	v_max_f32_e32 v0, v46, v46
	v_mul_f32_e32 v46, v42, v42
	v_max_f32_e32 v43, 0, v43
	v_max_f32_e32 v44, 0, v44
	v_max_f32_e32 v51, 0, v51
	v_max_f32_e32 v52, 0, v57
	v_max_f32_e32 v53, 0, v53
	v_max_f32_e32 v0, 0, v0
	v_max_f32_e32 v42, 0, v47
	v_mul_f32_e32 v47, v43, v43
	v_max_f32_e32 v43, v48, v48
	v_mul_f32_e32 v48, v44, v44
	v_mul_f32_e32 v51, v51, v51
	v_mul_f32_e32 v52, v52, v52
	v_mul_f32_e32 v53, v53, v53
	v_mul_f32_e32 v0, v0, v0
	v_mul_f32_e32 v42, v42, v42
	v_max_f32_e32 v43, 0, v43
	v_max_f32_e32 v44, 0, v49
	v_max_f32_e32 v34, 0, v34
	v_cvt_pk_bf16_f32 v51, v51, v52
	v_cvt_pk_bf16_f32 v52, v54, v55
	v_cvt_pk_bf16_f32 v53, v56, v53
	global_store_dwordx4 v[62:63], v[50:53], off offset:256
	s_nop 1
	v_mul_f32_e32 v43, v43, v43
	v_mul_f32_e32 v44, v44, v44
	v_cvt_pk_bf16_f32 v42, v0, v42
	s_mov_b32 s6, 0x240000
	v_max_f32_e32 v0, v38, v38
	v_mul_f32_e32 v38, v34, v34
	v_max_f32_e32 v45, 0, v45
	v_cvt_pk_bf16_f32 v43, v43, v44
	v_cvt_pk_bf16_f32 v44, v46, v47
	v_add_co_u32_e32 v46, vcc, s6, v142
	v_max_f32_e32 v0, 0, v0
	v_max_f32_e32 v34, 0, v39
	v_mul_f32_e32 v45, v45, v45
	v_addc_co_u32_e32 v47, vcc, 0, v143, vcc
	v_mul_f32_e32 v0, v0, v0
	v_max_f32_e32 v35, 0, v35
	v_mul_f32_e32 v34, v34, v34
	v_max_f32_e32 v36, 0, v36
	v_max_f32_e32 v26, 0, v26
	v_cvt_pk_bf16_f32 v45, v48, v45
	global_store_dwordx4 v[46:47], v[42:45], off
	s_nop 1
	v_mul_f32_e32 v39, v35, v35
	v_max_f32_e32 v35, v40, v40
	v_mul_f32_e32 v40, v36, v36
	v_cvt_pk_bf16_f32 v34, v0, v34
	v_max_f32_e32 v0, v30, v30
	v_mul_f32_e32 v30, v26, v26
	v_max_f32_e32 v27, 0, v27
	v_max_f32_e32 v28, 0, v28
	v_max_f32_e32 v35, 0, v35
	v_max_f32_e32 v36, 0, v41
	v_max_f32_e32 v37, 0, v37
	v_max_f32_e32 v0, 0, v0
	v_max_f32_e32 v26, 0, v31
	v_mul_f32_e32 v31, v27, v27
	v_max_f32_e32 v27, v32, v32
	v_mul_f32_e32 v32, v28, v28
	v_mul_f32_e32 v35, v35, v35
	v_mul_f32_e32 v36, v36, v36
	v_mul_f32_e32 v37, v37, v37
	v_mul_f32_e32 v0, v0, v0
	v_mul_f32_e32 v26, v26, v26
	v_max_f32_e32 v27, 0, v27
	v_max_f32_e32 v28, 0, v33
	v_max_f32_e32 v18, 0, v18
	v_cvt_pk_bf16_f32 v35, v35, v36
	v_cvt_pk_bf16_f32 v36, v38, v39
	v_cvt_pk_bf16_f32 v37, v40, v37
	global_store_dwordx4 v[46:47], v[34:37], off offset:256
	s_nop 1
	v_mul_f32_e32 v27, v27, v27
	v_mul_f32_e32 v28, v28, v28
	v_cvt_pk_bf16_f32 v26, v0, v26
	s_mov_b32 s6, 0x280000
	v_max_f32_e32 v0, v22, v22
	v_mul_f32_e32 v22, v18, v18
	v_max_f32_e32 v29, 0, v29
	v_cvt_pk_bf16_f32 v27, v27, v28
	v_cvt_pk_bf16_f32 v28, v30, v31
	v_add_co_u32_e32 v30, vcc, s6, v142
	v_max_f32_e32 v0, 0, v0
	v_max_f32_e32 v18, 0, v23
	v_mul_f32_e32 v29, v29, v29
	v_addc_co_u32_e32 v31, vcc, 0, v143, vcc
	v_mul_f32_e32 v0, v0, v0
	v_max_f32_e32 v19, 0, v19
	v_mul_f32_e32 v18, v18, v18
	v_max_f32_e32 v20, 0, v20
	v_max_f32_e32 v10, 0, v10
	v_max_f32_e32 v11, 0, v11
	v_max_f32_e32 v12, 0, v12
	v_cvt_pk_bf16_f32 v29, v32, v29
	global_store_dwordx4 v[30:31], v[26:29], off
	s_nop 1
	v_mul_f32_e32 v23, v19, v19
	v_max_f32_e32 v19, v24, v24
	v_mul_f32_e32 v24, v20, v20
	v_cvt_pk_bf16_f32 v18, v0, v18
	v_max_f32_e32 v0, v14, v14
	v_mul_f32_e32 v14, v10, v10
	v_max_f32_e32 v10, v15, v15
	v_mul_f32_e32 v15, v11, v11
	v_max_f32_e32 v11, v16, v16
	v_mul_f32_e32 v16, v12, v12
	v_max_f32_e32 v19, 0, v19
	v_max_f32_e32 v20, 0, v25
	v_max_f32_e32 v21, 0, v21
	v_max_f32_e32 v0, 0, v0
	v_max_f32_e32 v10, 0, v10
	v_max_f32_e32 v11, 0, v11
	v_max_f32_e32 v12, 0, v17
	v_mul_f32_e32 v19, v19, v19
	v_mul_f32_e32 v20, v20, v20
	v_mul_f32_e32 v21, v21, v21
	v_mul_f32_e32 v0, v0, v0
	v_mul_f32_e32 v10, v10, v10
	v_mul_f32_e32 v11, v11, v11
	v_mul_f32_e32 v12, v12, v12
	s_mov_b32 s6, 0x2c0000
	v_max_f32_e32 v2, 0, v2
	v_max_f32_e32 v3, 0, v3
	v_max_f32_e32 v4, 0, v4
	v_cvt_pk_bf16_f32 v19, v19, v20
	v_cvt_pk_bf16_f32 v20, v22, v23
	v_cvt_pk_bf16_f32 v21, v24, v21
	global_store_dwordx4 v[30:31], v[18:21], off offset:256
	s_nop 1
	v_cvt_pk_bf16_f32 v10, v0, v10
	v_cvt_pk_bf16_f32 v11, v11, v12
	v_cvt_pk_bf16_f32 v12, v14, v15
	v_add_co_u32_e32 v14, vcc, s6, v142
	v_max_f32_e32 v0, v6, v6
	v_mul_f32_e32 v6, v2, v2
	v_max_f32_e32 v2, v7, v7
	v_mul_f32_e32 v7, v3, v3
	v_max_f32_e32 v3, v8, v8
	v_mul_f32_e32 v8, v4, v4
	v_max_f32_e32 v13, 0, v13
	v_addc_co_u32_e32 v15, vcc, 0, v143, vcc
	v_max_f32_e32 v2, 0, v2
	v_max_f32_e32 v3, 0, v3
	v_max_f32_e32 v4, 0, v9
	v_max_f32_e32 v5, 0, v5
	v_mul_f32_e32 v13, v13, v13
	v_max_f32_e32 v0, 0, v0
	v_mul_f32_e32 v2, v2, v2
	v_mul_f32_e32 v3, v3, v3
	v_mul_f32_e32 v4, v4, v4
	v_mul_f32_e32 v5, v5, v5
	s_andn2_b64 vcc, exec, s[40:41]
	s_mov_b64 s[6:7], -1
	s_mov_b32 s70, 0x2aaaaaab
	s_mov_b64 s[72:73], 0x26000
	v_cvt_pk_bf16_f32 v13, v16, v13
	global_store_dwordx4 v[14:15], v[10:13], off
	s_nop 1
	v_mul_f32_e32 v0, v0, v0
	v_cvt_pk_bf16_f32 v2, v0, v2
	v_cvt_pk_bf16_f32 v3, v3, v4
	v_cvt_pk_bf16_f32 v4, v6, v7
	v_cvt_pk_bf16_f32 v5, v8, v5
	global_store_dwordx4 v[14:15], v[2:5], off offset:256
	s_nop 1
	s_cbranch_vccnz .LBB0_28
	s_andn2_b64 vcc, exec, s[28:29]
	s_cbranch_vccnz .LBB0_27
	s_barrier
	s_branch .LBB0_27

.LBB0_409:
	s_and_b64 vcc, exec, s[4:5]
	s_cbranch_vccz .LBB0_577
	s_movk_i32 s4, 0x4800
	v_cmp_gt_i32_e32 vcc, s4, v164
	s_and_saveexec_b64 s[4:5], vcc
	s_cbranch_execz .LBB0_413
	s_load_dwordx4 s[40:43], s[0:1], 0x48
	v_ashrrev_i32_e32 v165, 31, v164
	s_waitcnt vmcnt(0)
	v_lshlrev_b32_e32 v5, 2, v164
	s_mov_b32 s6, 0
	s_waitcnt lgkmcnt(0)
.Lsilu_loop:
	global_load_dword v12, v5, s[40:41]
	v_add_u32_e32 v7, 0x2000, v5
	global_load_dword v13, v7, s[40:41]
	v_add_u32_e32 v6, 0x4000, v5
	global_load_dword v14, v6, s[40:41]
	v_add_u32_e32 v7, 0x6000, v5
	global_load_dword v15, v7, s[40:41]
	v_add_u32_e32 v6, 0x8000, v5
	global_load_dword v16, v6, s[40:41]
	v_add_u32_e32 v7, 0xa000, v5
	global_load_dword v17, v7, s[40:41]
	v_add_u32_e32 v6, 0xc000, v5
	global_load_dword v18, v6, s[40:41]
	v_add_u32_e32 v7, 0xe000, v5
	global_load_dword v19, v7, s[40:41]
	global_load_dword v20, v5, s[42:43]
	v_add_u32_e32 v2, 0x8000, v5
	s_waitcnt vmcnt(8)
	v_mul_f32_e32 v6, 0xbfb8aa3b, v12
	v_exp_f32_e32 v6, v6
	s_nop 0
	v_add_f32_e32 v6, 1.0, v6
	v_div_scale_f32 v7, s[8:9], v6, v6, v12
	v_rcp_f32_e32 v8, v7
	v_div_scale_f32 v9, vcc, v12, v6, v12
	v_fma_f32 v10, -v7, v8, 1.0
	v_fmac_f32_e32 v8, v10, v8
	v_mul_f32_e32 v10, v9, v8
	v_fma_f32 v11, -v7, v10, v9
	v_fmac_f32_e32 v10, v11, v8
	v_fma_f32 v7, -v7, v10, v9
	v_div_fmas_f32 v7, v7, v8, v10
	v_div_fixup_f32 v0, v7, v6, v12
	ds_write_b32 v5, v0
	s_waitcnt vmcnt(7)
	v_mul_f32_e32 v6, 0xbfb8aa3b, v13
	v_exp_f32_e32 v6, v6
	s_nop 0
	v_add_f32_e32 v6, 1.0, v6
	v_div_scale_f32 v7, s[8:9], v6, v6, v13
	v_rcp_f32_e32 v8, v7
	v_div_scale_f32 v9, vcc, v13, v6, v13
	v_fma_f32 v10, -v7, v8, 1.0
	v_fmac_f32_e32 v8, v10, v8
	v_mul_f32_e32 v10, v9, v8
	v_fma_f32 v11, -v7, v10, v9
	v_fmac_f32_e32 v10, v11, v8
	v_fma_f32 v7, -v7, v10, v9
	v_div_fmas_f32 v7, v7, v8, v10
	v_div_fixup_f32 v0, v7, v6, v13
	ds_write_b32 v5, v0 offset:8192
	s_waitcnt vmcnt(6)
	v_mul_f32_e32 v6, 0xbfb8aa3b, v14
	v_exp_f32_e32 v6, v6
	s_nop 0
	v_add_f32_e32 v6, 1.0, v6
	v_div_scale_f32 v7, s[8:9], v6, v6, v14
	v_rcp_f32_e32 v8, v7
	v_div_scale_f32 v9, vcc, v14, v6, v14
	v_fma_f32 v10, -v7, v8, 1.0
	v_fmac_f32_e32 v8, v10, v8
	v_mul_f32_e32 v10, v9, v8
	v_fma_f32 v11, -v7, v10, v9
	v_fmac_f32_e32 v10, v11, v8
	v_fma_f32 v7, -v7, v10, v9
	v_div_fmas_f32 v7, v7, v8, v10
	v_div_fixup_f32 v0, v7, v6, v14
	ds_write_b32 v5, v0 offset:16384
	s_waitcnt vmcnt(5)
	v_mul_f32_e32 v6, 0xbfb8aa3b, v15
	v_exp_f32_e32 v6, v6
	s_nop 0
	v_add_f32_e32 v6, 1.0, v6
	v_div_scale_f32 v7, s[8:9], v6, v6, v15
	v_rcp_f32_e32 v8, v7
	v_div_scale_f32 v9, vcc, v15, v6, v15
	v_fma_f32 v10, -v7, v8, 1.0
	v_fmac_f32_e32 v8, v10, v8
	v_mul_f32_e32 v10, v9, v8
	v_fma_f32 v11, -v7, v10, v9
	v_fmac_f32_e32 v10, v11, v8
	v_fma_f32 v7, -v7, v10, v9
	v_div_fmas_f32 v7, v7, v8, v10
	v_div_fixup_f32 v0, v7, v6, v15
	ds_write_b32 v5, v0 offset:24576
	s_waitcnt vmcnt(4)
	v_mul_f32_e32 v6, 0xbfb8aa3b, v16
	v_exp_f32_e32 v6, v6
	s_nop 0
	v_add_f32_e32 v6, 1.0, v6
	v_div_scale_f32 v7, s[8:9], v6, v6, v16
	v_rcp_f32_e32 v8, v7
	v_div_scale_f32 v9, vcc, v16, v6, v16
	v_fma_f32 v10, -v7, v8, 1.0
	v_fmac_f32_e32 v8, v10, v8
	v_mul_f32_e32 v10, v9, v8
	v_fma_f32 v11, -v7, v10, v9
	v_fmac_f32_e32 v10, v11, v8
	v_fma_f32 v7, -v7, v10, v9
	v_div_fmas_f32 v7, v7, v8, v10
	v_div_fixup_f32 v0, v7, v6, v16
	ds_write_b32 v5, v0 offset:32768
	s_waitcnt vmcnt(3)
	v_mul_f32_e32 v6, 0xbfb8aa3b, v17
	v_exp_f32_e32 v6, v6
	s_nop 0
	v_add_f32_e32 v6, 1.0, v6
	v_div_scale_f32 v7, s[8:9], v6, v6, v17
	v_rcp_f32_e32 v8, v7
	v_div_scale_f32 v9, vcc, v17, v6, v17
	v_fma_f32 v10, -v7, v8, 1.0
	v_fmac_f32_e32 v8, v10, v8
	v_mul_f32_e32 v10, v9, v8
	v_fma_f32 v11, -v7, v10, v9
	v_fmac_f32_e32 v10, v11, v8
	v_fma_f32 v7, -v7, v10, v9
	v_div_fmas_f32 v7, v7, v8, v10
	v_div_fixup_f32 v0, v7, v6, v17
	ds_write_b32 v5, v0 offset:40960
	s_waitcnt vmcnt(2)
	v_mul_f32_e32 v6, 0xbfb8aa3b, v18
	v_exp_f32_e32 v6, v6
	s_nop 0
	v_add_f32_e32 v6, 1.0, v6
	v_div_scale_f32 v7, s[8:9], v6, v6, v18
	v_rcp_f32_e32 v8, v7
	v_div_scale_f32 v9, vcc, v18, v6, v18
	v_fma_f32 v10, -v7, v8, 1.0
	v_fmac_f32_e32 v8, v10, v8
	v_mul_f32_e32 v10, v9, v8
	v_fma_f32 v11, -v7, v10, v9
	v_fmac_f32_e32 v10, v11, v8
	v_fma_f32 v7, -v7, v10, v9
	v_div_fmas_f32 v7, v7, v8, v10
	v_div_fixup_f32 v0, v7, v6, v18
	ds_write_b32 v5, v0 offset:49152
	s_waitcnt vmcnt(1)
	v_mul_f32_e32 v6, 0xbfb8aa3b, v19
	v_exp_f32_e32 v6, v6
	s_nop 0
	v_add_f32_e32 v6, 1.0, v6
	v_div_scale_f32 v7, s[8:9], v6, v6, v19
	v_rcp_f32_e32 v8, v7
	v_div_scale_f32 v9, vcc, v19, v6, v19
	v_fma_f32 v10, -v7, v8, 1.0
	v_fmac_f32_e32 v8, v10, v8
	v_mul_f32_e32 v10, v9, v8
	v_fma_f32 v11, -v7, v10, v9
	v_fmac_f32_e32 v10, v11, v8
	v_fma_f32 v7, -v7, v10, v9
	v_div_fmas_f32 v7, v7, v8, v10
	v_div_fixup_f32 v0, v7, v6, v19
	ds_write_b32 v5, v0 offset:57344
	s_waitcnt vmcnt(0)
	v_mul_f32_e32 v6, 0xbfb8aa3b, v20
	v_exp_f32_e32 v6, v6
	s_nop 0
	v_add_f32_e32 v6, 1.0, v6
	v_div_scale_f32 v7, s[8:9], v6, v6, v20
	v_rcp_f32_e32 v8, v7
	v_div_scale_f32 v9, vcc, v20, v6, v20
	v_fma_f32 v10, -v7, v8, 1.0
	v_fmac_f32_e32 v8, v10, v8
	v_mul_f32_e32 v10, v9, v8
	v_fma_f32 v11, -v7, v10, v9
	v_fmac_f32_e32 v10, v11, v8
	v_fma_f32 v7, -v7, v10, v9
	v_div_fmas_f32 v7, v7, v8, v10
	v_div_fixup_f32 v0, v7, v6, v20
	ds_write_b32 v2, v0 offset:32768
	v_add_u32_e32 v5, 0x800, v5
	s_add_i32 s6, s6, 1
	s_cmp_lt_u32 s6, 4
	s_cbranch_scc1 .Lsilu_loop

.LBB0_586:
	v_readlane_b32 s6, v253, 16
	v_readlane_b32 s7, v253, 17
	v_readlane_b32 s8, v254, 40
	s_nop 3
	global_load_dword v0, v1, s[6:7] sc1
	v_readlane_b32 s6, v253, 18
	v_readlane_b32 s7, v253, 19
	s_waitcnt lgkmcnt(0)
	s_nop 3
	global_load_dword v2, v1, s[6:7] sc1
	v_readlane_b32 s6, v253, 20
	v_readlane_b32 s7, v253, 21
	s_nop 4
	global_load_dword v3, v1, s[6:7] sc1
	v_readlane_b32 s6, v253, 22
	v_readlane_b32 s7, v253, 23
	s_nop 4
	global_load_dword v4, v1, s[6:7] sc1
	v_readlane_b32 s6, v253, 24
	v_readlane_b32 s7, v253, 25
	s_nop 4
	global_load_dword v5, v1, s[6:7] sc1
	v_readlane_b32 s6, v253, 26
	v_readlane_b32 s7, v253, 27
	s_nop 4
	global_load_dword v6, v1, s[6:7] sc1
	v_readlane_b32 s6, v253, 28
	v_readlane_b32 s7, v253, 29
	s_nop 4
	global_load_dword v7, v1, s[6:7] sc1
	v_readlane_b32 s6, v253, 30
	v_readlane_b32 s7, v253, 31
	s_nop 4
	global_load_dword v8, v1, s[6:7] sc1
	v_readlane_b32 s6, v253, 32
	v_readlane_b32 s7, v253, 33
	s_nop 4
	global_load_dword v9, v1, s[6:7] sc1
	v_readlane_b32 s6, v253, 34
	v_readlane_b32 s7, v253, 35
	s_nop 4
	global_load_dword v10, v1, s[6:7] sc1
	v_readlane_b32 s6, v253, 36
	v_readlane_b32 s7, v253, 37
	s_nop 4
	global_load_dword v11, v1, s[6:7] sc1
	v_readlane_b32 s6, v253, 38
	v_readlane_b32 s7, v253, 39
	s_nop 4
	global_load_dword v12, v1, s[6:7] sc1
	v_readlane_b32 s6, v253, 40
	v_readlane_b32 s7, v253, 41
	s_nop 4
	global_load_dword v13, v1, s[6:7] sc1
	v_readlane_b32 s6, v253, 42
	v_readlane_b32 s7, v253, 43
	s_nop 4
	global_load_dword v14, v1, s[6:7] sc1
	v_readlane_b32 s6, v253, 44
	v_readlane_b32 s7, v253, 45
	s_nop 4
	global_load_dword v15, v1, s[6:7] sc1
	v_readlane_b32 s6, v253, 46
	v_readlane_b32 s7, v253, 47
	s_nop 4
	global_load_dword v16, v1, s[6:7] sc1
	s_mov_b64 s[6:7], -1
	s_waitcnt vmcnt(0)
	v_add_u32_e32 v17, v2, v0
	v_add_u32_e32 v17, v17, v3
	v_add_u32_e32 v17, v17, v4
	v_add_u32_e32 v17, v17, v5
	v_add_u32_e32 v17, v17, v6
	v_add_u32_e32 v17, v17, v7
	v_add_u32_e32 v17, v17, v8
	v_add_u32_e32 v17, v17, v9
	v_add_u32_e32 v17, v17, v10
	v_add_u32_e32 v17, v17, v11
	v_add_u32_e32 v17, v17, v12
	v_add_u32_e32 v17, v17, v13
	v_add_u32_e32 v17, v17, v14
	v_add_u32_e32 v17, v17, v15
	v_add_u32_e32 v17, v17, v16
	v_cmp_eq_u32_e32 vcc, s8, v17
	s_mov_b64 s[8:9], -1
	s_cbranch_vccnz .LBB0_585
	s_and_b32 s6, s12, 0xff
	s_cmp_eq_u32 s6, 0
	s_mov_b64 s[6:7], -1
	s_mov_b64 s[10:11], -1
	s_sleep 1
	s_cbranch_scc0 .LBB0_590
	v_readlane_b32 s6, v253, 14
	v_readlane_b32 s7, v253, 15
	s_nop 4
	global_load_dword v17, v1, s[6:7] sc1
	s_waitcnt vmcnt(0)
	v_cmp_eq_u32_e32 vcc, 0, v17
	s_cbranch_vccnz .LBB0_592
	s_mov_b64 s[10:11], 0
	s_mov_b64 s[6:7], -1
